# GEMM phases: one static s_setprio 1 for waves 4-7 at phase start (P1, P3/P4), reset to 0 for LRU/attention
# baseline (speedup 1.0000x reference)
.LBB0_142:
	v_readfirstlane_b32 s32, v254
	s_cmpk_lt_u32 s32, 0x100
	s_cbranch_scc1 .Lgprio_1
	s_setprio 1

.LBB0_334:
	s_setprio 0
	s_cmp_lt_i32 s68, 3
	s_cselect_b64 s[0:1], -1, 0
	s_add_u32 s28, s78, 0x1e800000
	s_addc_u32 s29, s79, 0
	s_add_u32 s30, s78, 0x1e900000
	s_addc_u32 s31, s79, 0
	s_and_b64 s[82:83], s[0:1], s[4:5]
	s_andn2_b64 vcc, exec, s[82:83]
	s_cbranch_vccnz .LBB0_432
	v_readlane_b32 s0, v255, 5
	v_readlane_b32 s1, v255, 6
	s_add_u32 s40, s0, 0xb8
	s_addc_u32 s41, s1, 0
	v_mov_b32_e32 v76, v254
	s_cmpk_lt_i32 s2, 0x100
	s_nop 0
	v_readfirstlane_b32 s0, v76
	s_cbranch_scc1 .LBB0_337
	s_load_dword s3, s[40:41], 0x0
	s_cbranch_execz .LBB0_338
	s_branch .LBB0_370
